# strategy 4 A/B: static s_setprio 1 for the OLDER wave half (waves 0-3) in the GEMM phases, flips deleted
# speedup vs baseline: 1.0070x; 1.0070x over previous
.LBB0_210:
	s_cmp_lg_u32 s3, 0
	s_cbranch_scc1 .Lold_0
	s_setprio 1

.LBB0_327:
	s_cmp_lg_u32 s0, 0
	s_cbranch_scc1 .Lold_1
	s_setprio 1

.LBB0_454:
	s_cmp_lg_u32 s10, 0
	s_cbranch_scc1 .Lold_2
	s_setprio 1

.LBB0_724:
	s_cmp_lg_u32 s2, 0
	s_cbranch_scc1 .Lold_3
	s_setprio 1

.LBB0_1327:
	s_cmp_lg_u32 s14, 0
	s_cbranch_scc1 .Lold_8
	s_setprio 1

.LBB0_1579:
	s_cmp_lg_u32 s12, 0
	s_cbranch_scc1 .Lold_10
	s_setprio 1
